# M_GATE sigmoid: bias v_movs removed, bias add / -log2e mul / +1 / x255 packed into v_pk f32 ops (bit-identical)
# speedup vs baseline: 1.0122x; 1.0052x over previous
.LBB0_251:
	s_and_b64 vcc, exec, s[50:51]
	s_cbranch_vccz .LBB0_253
	v_add_u32_e32 v150, s10, v146
	v_ashrrev_i32_e32 v151, 31, v150
	v_lshl_add_u64 v[126:127], v[150:151], 2, s[98:99]
	global_load_dwordx4 v[228:231], v[126:127], off
	global_load_dwordx4 v[232:235], v[126:127], off offset:16
	s_waitcnt vmcnt(0)
	v_pk_add_f32 v[122:123], v[176:177], v[228:229]
	v_pk_add_f32 v[124:125], v[172:173], v[230:231]
	v_pk_add_f32 v[126:127], v[188:189], v[232:233]
	v_pk_add_f32 v[128:129], v[186:187], v[234:235]
	s_mov_b32 vcc_lo, 0xbfb8aa3b
	v_pk_mul_f32 v[122:123], v[122:123], vcc op_sel_hi:[1,0]
	v_pk_mul_f32 v[124:125], v[124:125], vcc op_sel_hi:[1,0]
	v_pk_mul_f32 v[126:127], v[126:127], vcc op_sel_hi:[1,0]
	v_pk_mul_f32 v[128:129], v[128:129], vcc op_sel_hi:[1,0]
	v_exp_f32_e32 v122, v122
	v_exp_f32_e32 v126, v126
	v_exp_f32_e32 v123, v123
	v_exp_f32_e32 v127, v127
	v_exp_f32_e32 v124, v124
	v_exp_f32_e32 v128, v128
	v_exp_f32_e32 v125, v125
	v_exp_f32_e32 v129, v129
	s_mov_b32 vcc_lo, 1.0
	v_pk_add_f32 v[122:123], v[122:123], vcc op_sel_hi:[1,0]
	v_pk_add_f32 v[124:125], v[124:125], vcc op_sel_hi:[1,0]
	v_pk_add_f32 v[126:127], v[126:127], vcc op_sel_hi:[1,0]
	v_pk_add_f32 v[128:129], v[128:129], vcc op_sel_hi:[1,0]
	v_rcp_f32_e32 v122, v122
	v_rcp_f32_e32 v126, v126
	v_rcp_f32_e32 v123, v123
	v_rcp_f32_e32 v127, v127
	v_rcp_f32_e32 v124, v124
	v_rcp_f32_e32 v128, v128
	v_rcp_f32_e32 v125, v125
	v_rcp_f32_e32 v129, v129
	s_mov_b32 vcc_lo, 0x437f0000
	v_pk_mul_f32 v[122:123], v[122:123], vcc op_sel_hi:[1,0]
	v_pk_mul_f32 v[124:125], v[124:125], vcc op_sel_hi:[1,0]
	v_pk_mul_f32 v[126:127], v[126:127], vcc op_sel_hi:[1,0]
	v_pk_mul_f32 v[128:129], v[128:129], vcc op_sel_hi:[1,0]
	v_rndne_f32_e32 v122, v122
	v_rndne_f32_e32 v126, v126
	v_rndne_f32_e32 v123, v123
	v_rndne_f32_e32 v127, v127
	v_rndne_f32_e32 v124, v124
	v_rndne_f32_e32 v128, v128
	v_rndne_f32_e32 v125, v125
	v_rndne_f32_e32 v129, v129
	v_cvt_u32_f32_e32 v122, v122
	v_cvt_u32_f32_e32 v126, v126
	v_cvt_u32_f32_e32 v123, v123
	v_cvt_u32_f32_e32 v127, v127
	v_cvt_u32_f32_sdwa v124, v124 dst_sel:WORD_1 dst_unused:UNUSED_PAD src0_sel:DWORD
	v_cvt_u32_f32_sdwa v128, v128 dst_sel:WORD_1 dst_unused:UNUSED_PAD src0_sel:DWORD
	v_cvt_u32_f32_sdwa v125, v125 dst_sel:BYTE_3 dst_unused:UNUSED_PAD src0_sel:DWORD
	v_cvt_u32_f32_sdwa v129, v129 dst_sel:BYTE_3 dst_unused:UNUSED_PAD src0_sel:DWORD
	v_lshl_or_b32 v122, v123, 8, v122
	v_lshl_or_b32 v123, v127, 8, v126
	v_or3_b32 v122, v122, v124, v125
	v_or3_b32 v123, v123, v128, v129
	v_lshl_add_u64 v[124:125], v[162:163], 0, v[150:151]
	global_store_dwordx2 v[124:125], v[122:123], off

.LBB0_308:
	s_and_b64 vcc, exec, s[50:51]
	s_cbranch_vccz .LBB0_310
	v_add_u32_e32 v168, s10, v122
	v_ashrrev_i32_e32 v169, 31, v168
	v_lshl_add_u64 v[118:119], v[168:169], 2, s[98:99]
	global_load_dwordx4 v[236:239], v[118:119], off
	global_load_dwordx2 v[240:241], v[118:119], off offset:16
	global_load_dwordx2 v[206:207], v[118:119], off offset:24
	s_waitcnt vmcnt(0)
	v_pk_add_f32 v[114:115], v[172:173], v[236:237]
	v_pk_add_f32 v[116:117], v[124:125], v[238:239]
	v_pk_add_f32 v[118:119], v[178:179], v[240:241]
	v_pk_add_f32 v[120:121], v[176:177], v[206:207]
	s_mov_b32 vcc_lo, 0xbfb8aa3b
	v_pk_mul_f32 v[114:115], v[114:115], vcc op_sel_hi:[1,0]
	v_pk_mul_f32 v[116:117], v[116:117], vcc op_sel_hi:[1,0]
	v_pk_mul_f32 v[118:119], v[118:119], vcc op_sel_hi:[1,0]
	v_pk_mul_f32 v[120:121], v[120:121], vcc op_sel_hi:[1,0]
	v_exp_f32_e32 v114, v114
	v_exp_f32_e32 v118, v118
	v_exp_f32_e32 v115, v115
	v_exp_f32_e32 v119, v119
	v_exp_f32_e32 v116, v116
	v_exp_f32_e32 v120, v120
	v_exp_f32_e32 v117, v117
	v_exp_f32_e32 v121, v121
	s_mov_b32 vcc_lo, 1.0
	v_pk_add_f32 v[114:115], v[114:115], vcc op_sel_hi:[1,0]
	v_pk_add_f32 v[116:117], v[116:117], vcc op_sel_hi:[1,0]
	v_pk_add_f32 v[118:119], v[118:119], vcc op_sel_hi:[1,0]
	v_pk_add_f32 v[120:121], v[120:121], vcc op_sel_hi:[1,0]
	v_rcp_f32_e32 v114, v114
	v_rcp_f32_e32 v118, v118
	v_rcp_f32_e32 v115, v115
	v_rcp_f32_e32 v119, v119
	v_rcp_f32_e32 v116, v116
	v_rcp_f32_e32 v120, v120
	v_rcp_f32_e32 v117, v117
	v_rcp_f32_e32 v121, v121
	s_mov_b32 vcc_lo, 0x437f0000
	v_pk_mul_f32 v[114:115], v[114:115], vcc op_sel_hi:[1,0]
	v_pk_mul_f32 v[116:117], v[116:117], vcc op_sel_hi:[1,0]
	v_pk_mul_f32 v[118:119], v[118:119], vcc op_sel_hi:[1,0]
	v_pk_mul_f32 v[120:121], v[120:121], vcc op_sel_hi:[1,0]
	v_rndne_f32_e32 v114, v114
	v_rndne_f32_e32 v118, v118
	v_rndne_f32_e32 v115, v115
	v_rndne_f32_e32 v119, v119
	v_rndne_f32_e32 v116, v116
	v_rndne_f32_e32 v120, v120
	v_rndne_f32_e32 v117, v117
	v_rndne_f32_e32 v121, v121
	v_cvt_u32_f32_e32 v114, v114
	v_cvt_u32_f32_e32 v118, v118
	v_cvt_u32_f32_e32 v115, v115
	v_cvt_u32_f32_e32 v119, v119
	v_cvt_u32_f32_sdwa v116, v116 dst_sel:WORD_1 dst_unused:UNUSED_PAD src0_sel:DWORD
	v_cvt_u32_f32_sdwa v120, v120 dst_sel:WORD_1 dst_unused:UNUSED_PAD src0_sel:DWORD
	v_cvt_u32_f32_sdwa v117, v117 dst_sel:BYTE_3 dst_unused:UNUSED_PAD src0_sel:DWORD
	v_cvt_u32_f32_sdwa v121, v121 dst_sel:BYTE_3 dst_unused:UNUSED_PAD src0_sel:DWORD
	v_lshl_or_b32 v114, v115, 8, v114
	v_lshl_or_b32 v115, v119, 8, v118
	v_or3_b32 v114, v114, v116, v117
	v_or3_b32 v115, v115, v120, v121
	v_lshl_add_u64 v[116:117], v[162:163], 0, v[168:169]
	global_store_dwordx2 v[116:117], v[114:115], off

.LBB0_381:
	s_and_b64 vcc, exec, s[50:51]
	s_cbranch_vccz .LBB0_383
	v_add_u32_e32 v120, s10, v146
	v_ashrrev_i32_e32 v121, 31, v120
	v_pk_add_f32 v[106:107], v[174:175], v[228:229]
	v_pk_add_f32 v[108:109], v[162:163], v[230:231]
	v_pk_add_f32 v[110:111], v[178:179], v[232:233]
	v_pk_add_f32 v[112:113], v[176:177], v[234:235]
	s_mov_b32 vcc_lo, 0xbfb8aa3b
	v_pk_mul_f32 v[106:107], v[106:107], vcc op_sel_hi:[1,0]
	v_pk_mul_f32 v[108:109], v[108:109], vcc op_sel_hi:[1,0]
	v_pk_mul_f32 v[110:111], v[110:111], vcc op_sel_hi:[1,0]
	v_pk_mul_f32 v[112:113], v[112:113], vcc op_sel_hi:[1,0]
	v_exp_f32_e32 v106, v106
	v_exp_f32_e32 v110, v110
	v_exp_f32_e32 v107, v107
	v_exp_f32_e32 v111, v111
	v_exp_f32_e32 v108, v108
	v_exp_f32_e32 v112, v112
	v_exp_f32_e32 v109, v109
	v_exp_f32_e32 v113, v113
	s_mov_b32 vcc_lo, 1.0
	v_pk_add_f32 v[106:107], v[106:107], vcc op_sel_hi:[1,0]
	v_pk_add_f32 v[108:109], v[108:109], vcc op_sel_hi:[1,0]
	v_pk_add_f32 v[110:111], v[110:111], vcc op_sel_hi:[1,0]
	v_pk_add_f32 v[112:113], v[112:113], vcc op_sel_hi:[1,0]
	v_rcp_f32_e32 v106, v106
	v_rcp_f32_e32 v110, v110
	v_rcp_f32_e32 v107, v107
	v_rcp_f32_e32 v111, v111
	v_rcp_f32_e32 v108, v108
	v_rcp_f32_e32 v112, v112
	v_rcp_f32_e32 v109, v109
	v_rcp_f32_e32 v113, v113
	s_mov_b32 vcc_lo, 0x437f0000
	v_pk_mul_f32 v[106:107], v[106:107], vcc op_sel_hi:[1,0]
	v_pk_mul_f32 v[108:109], v[108:109], vcc op_sel_hi:[1,0]
	v_pk_mul_f32 v[110:111], v[110:111], vcc op_sel_hi:[1,0]
	v_pk_mul_f32 v[112:113], v[112:113], vcc op_sel_hi:[1,0]
	v_rndne_f32_e32 v106, v106
	v_rndne_f32_e32 v110, v110
	v_rndne_f32_e32 v107, v107
	v_rndne_f32_e32 v111, v111
	v_rndne_f32_e32 v108, v108
	v_rndne_f32_e32 v112, v112
	v_rndne_f32_e32 v109, v109
	v_rndne_f32_e32 v113, v113
	v_cvt_u32_f32_e32 v106, v106
	v_cvt_u32_f32_e32 v110, v110
	v_cvt_u32_f32_e32 v107, v107
	v_cvt_u32_f32_e32 v111, v111
	v_cvt_u32_f32_sdwa v108, v108 dst_sel:WORD_1 dst_unused:UNUSED_PAD src0_sel:DWORD
	v_cvt_u32_f32_sdwa v112, v112 dst_sel:WORD_1 dst_unused:UNUSED_PAD src0_sel:DWORD
	v_cvt_u32_f32_sdwa v109, v109 dst_sel:BYTE_3 dst_unused:UNUSED_PAD src0_sel:DWORD
	v_cvt_u32_f32_sdwa v113, v113 dst_sel:BYTE_3 dst_unused:UNUSED_PAD src0_sel:DWORD
	v_lshl_or_b32 v106, v107, 8, v106
	v_lshl_or_b32 v107, v111, 8, v110
	v_or3_b32 v106, v106, v108, v109
	v_or3_b32 v107, v107, v112, v113
	v_lshl_add_u64 v[108:109], v[152:153], 0, v[120:121]
	global_store_dwordx2 v[108:109], v[106:107], off

.LBB0_440:
	s_and_b64 vcc, exec, s[50:51]
	s_cbranch_vccz .LBB0_442
	v_add_u32_e32 v158, s10, v122
	v_ashrrev_i32_e32 v159, 31, v158
	v_pk_add_f32 v[98:99], v[108:109], v[236:237]
	v_pk_add_f32 v[100:101], v[106:107], v[238:239]
	v_pk_add_f32 v[102:103], v[164:165], v[240:241]
	v_pk_add_f32 v[104:105], v[162:163], v[206:207]
	s_mov_b32 vcc_lo, 0xbfb8aa3b
	v_pk_mul_f32 v[98:99], v[98:99], vcc op_sel_hi:[1,0]
	v_pk_mul_f32 v[100:101], v[100:101], vcc op_sel_hi:[1,0]
	v_pk_mul_f32 v[102:103], v[102:103], vcc op_sel_hi:[1,0]
	v_pk_mul_f32 v[104:105], v[104:105], vcc op_sel_hi:[1,0]
	v_exp_f32_e32 v98, v98
	v_exp_f32_e32 v102, v102
	v_exp_f32_e32 v99, v99
	v_exp_f32_e32 v103, v103
	v_exp_f32_e32 v100, v100
	v_exp_f32_e32 v104, v104
	v_exp_f32_e32 v101, v101
	v_exp_f32_e32 v105, v105
	s_mov_b32 vcc_lo, 1.0
	v_pk_add_f32 v[98:99], v[98:99], vcc op_sel_hi:[1,0]
	v_pk_add_f32 v[100:101], v[100:101], vcc op_sel_hi:[1,0]
	v_pk_add_f32 v[102:103], v[102:103], vcc op_sel_hi:[1,0]
	v_pk_add_f32 v[104:105], v[104:105], vcc op_sel_hi:[1,0]
	v_rcp_f32_e32 v98, v98
	v_rcp_f32_e32 v102, v102
	v_rcp_f32_e32 v99, v99
	v_rcp_f32_e32 v103, v103
	v_rcp_f32_e32 v100, v100
	v_rcp_f32_e32 v104, v104
	v_rcp_f32_e32 v101, v101
	v_rcp_f32_e32 v105, v105
	s_mov_b32 vcc_lo, 0x437f0000
	v_pk_mul_f32 v[98:99], v[98:99], vcc op_sel_hi:[1,0]
	v_pk_mul_f32 v[100:101], v[100:101], vcc op_sel_hi:[1,0]
	v_pk_mul_f32 v[102:103], v[102:103], vcc op_sel_hi:[1,0]
	v_pk_mul_f32 v[104:105], v[104:105], vcc op_sel_hi:[1,0]
	v_rndne_f32_e32 v98, v98
	v_rndne_f32_e32 v102, v102
	v_rndne_f32_e32 v99, v99
	v_rndne_f32_e32 v103, v103
	v_rndne_f32_e32 v100, v100
	v_rndne_f32_e32 v104, v104
	v_rndne_f32_e32 v101, v101
	v_rndne_f32_e32 v105, v105
	v_cvt_u32_f32_e32 v98, v98
	v_cvt_u32_f32_e32 v102, v102
	v_cvt_u32_f32_e32 v99, v99
	v_cvt_u32_f32_e32 v103, v103
	v_cvt_u32_f32_sdwa v100, v100 dst_sel:WORD_1 dst_unused:UNUSED_PAD src0_sel:DWORD
	v_cvt_u32_f32_sdwa v104, v104 dst_sel:WORD_1 dst_unused:UNUSED_PAD src0_sel:DWORD
	v_cvt_u32_f32_sdwa v101, v101 dst_sel:BYTE_3 dst_unused:UNUSED_PAD src0_sel:DWORD
	v_cvt_u32_f32_sdwa v105, v105 dst_sel:BYTE_3 dst_unused:UNUSED_PAD src0_sel:DWORD
	v_lshl_or_b32 v98, v99, 8, v98
	v_lshl_or_b32 v99, v103, 8, v102
	v_or3_b32 v98, v98, v100, v101
	v_or3_b32 v99, v99, v104, v105
	v_lshl_add_u64 v[100:101], v[152:153], 0, v[158:159]
	global_store_dwordx2 v[100:101], v[98:99], off

.LBB0_508:
	s_and_b64 vcc, exec, s[50:51]
	s_cbranch_vccz .LBB0_510
	v_add_u32_e32 v102, s10, v146
	v_ashrrev_i32_e32 v103, 31, v102
	v_pk_add_f32 v[90:91], v[158:159], v[228:229]
	v_pk_add_f32 v[92:93], v[120:121], v[230:231]
	v_pk_add_f32 v[94:95], v[162:163], v[232:233]
	v_pk_add_f32 v[96:97], v[160:161], v[234:235]
	s_mov_b32 vcc_lo, 0xbfb8aa3b
	v_pk_mul_f32 v[90:91], v[90:91], vcc op_sel_hi:[1,0]
	v_pk_mul_f32 v[92:93], v[92:93], vcc op_sel_hi:[1,0]
	v_pk_mul_f32 v[94:95], v[94:95], vcc op_sel_hi:[1,0]
	v_pk_mul_f32 v[96:97], v[96:97], vcc op_sel_hi:[1,0]
	v_exp_f32_e32 v90, v90
	v_exp_f32_e32 v94, v94
	v_exp_f32_e32 v91, v91
	v_exp_f32_e32 v95, v95
	v_exp_f32_e32 v92, v92
	v_exp_f32_e32 v96, v96
	v_exp_f32_e32 v93, v93
	v_exp_f32_e32 v97, v97
	s_mov_b32 vcc_lo, 1.0
	v_pk_add_f32 v[90:91], v[90:91], vcc op_sel_hi:[1,0]
	v_pk_add_f32 v[92:93], v[92:93], vcc op_sel_hi:[1,0]
	v_pk_add_f32 v[94:95], v[94:95], vcc op_sel_hi:[1,0]
	v_pk_add_f32 v[96:97], v[96:97], vcc op_sel_hi:[1,0]
	v_rcp_f32_e32 v90, v90
	v_rcp_f32_e32 v94, v94
	v_rcp_f32_e32 v91, v91
	v_rcp_f32_e32 v95, v95
	v_rcp_f32_e32 v92, v92
	v_rcp_f32_e32 v96, v96
	v_rcp_f32_e32 v93, v93
	v_rcp_f32_e32 v97, v97
	s_mov_b32 vcc_lo, 0x437f0000
	v_pk_mul_f32 v[90:91], v[90:91], vcc op_sel_hi:[1,0]
	v_pk_mul_f32 v[92:93], v[92:93], vcc op_sel_hi:[1,0]
	v_pk_mul_f32 v[94:95], v[94:95], vcc op_sel_hi:[1,0]
	v_pk_mul_f32 v[96:97], v[96:97], vcc op_sel_hi:[1,0]
	v_rndne_f32_e32 v90, v90
	v_rndne_f32_e32 v94, v94
	v_rndne_f32_e32 v91, v91
	v_rndne_f32_e32 v95, v95
	v_rndne_f32_e32 v92, v92
	v_rndne_f32_e32 v96, v96
	v_rndne_f32_e32 v93, v93
	v_rndne_f32_e32 v97, v97
	v_cvt_u32_f32_e32 v90, v90
	v_cvt_u32_f32_e32 v94, v94
	v_cvt_u32_f32_e32 v91, v91
	v_cvt_u32_f32_e32 v95, v95
	v_cvt_u32_f32_sdwa v92, v92 dst_sel:WORD_1 dst_unused:UNUSED_PAD src0_sel:DWORD
	v_cvt_u32_f32_sdwa v96, v96 dst_sel:WORD_1 dst_unused:UNUSED_PAD src0_sel:DWORD
	v_cvt_u32_f32_sdwa v93, v93 dst_sel:BYTE_3 dst_unused:UNUSED_PAD src0_sel:DWORD
	v_cvt_u32_f32_sdwa v97, v97 dst_sel:BYTE_3 dst_unused:UNUSED_PAD src0_sel:DWORD
	v_lshl_or_b32 v90, v91, 8, v90
	v_lshl_or_b32 v91, v95, 8, v94
	v_or3_b32 v90, v90, v92, v93
	v_or3_b32 v91, v91, v96, v97
	v_lshl_add_u64 v[92:93], v[108:109], 0, v[102:103]
	global_store_dwordx2 v[92:93], v[90:91], off

.LBB0_570:
	s_and_b64 vcc, exec, s[50:51]
	s_cbranch_vccz .LBB0_572
	v_add_u32_e32 v116, s10, v122
	v_ashrrev_i32_e32 v117, 31, v116
	v_pk_add_f32 v[82:83], v[92:93], v[236:237]
	v_pk_add_f32 v[84:85], v[90:91], v[238:239]
	v_pk_add_f32 v[86:87], v[124:125], v[240:241]
	v_pk_add_f32 v[88:89], v[120:121], v[206:207]
	s_mov_b32 vcc_lo, 0xbfb8aa3b
	v_pk_mul_f32 v[82:83], v[82:83], vcc op_sel_hi:[1,0]
	v_pk_mul_f32 v[84:85], v[84:85], vcc op_sel_hi:[1,0]
	v_pk_mul_f32 v[86:87], v[86:87], vcc op_sel_hi:[1,0]
	v_pk_mul_f32 v[88:89], v[88:89], vcc op_sel_hi:[1,0]
	v_exp_f32_e32 v82, v82
	v_exp_f32_e32 v86, v86
	v_exp_f32_e32 v83, v83
	v_exp_f32_e32 v87, v87
	v_exp_f32_e32 v84, v84
	v_exp_f32_e32 v88, v88
	v_exp_f32_e32 v85, v85
	v_exp_f32_e32 v89, v89
	s_mov_b32 vcc_lo, 1.0
	v_pk_add_f32 v[82:83], v[82:83], vcc op_sel_hi:[1,0]
	v_pk_add_f32 v[84:85], v[84:85], vcc op_sel_hi:[1,0]
	v_pk_add_f32 v[86:87], v[86:87], vcc op_sel_hi:[1,0]
	v_pk_add_f32 v[88:89], v[88:89], vcc op_sel_hi:[1,0]
	v_rcp_f32_e32 v82, v82
	v_rcp_f32_e32 v86, v86
	v_rcp_f32_e32 v83, v83
	v_rcp_f32_e32 v87, v87
	v_rcp_f32_e32 v84, v84
	v_rcp_f32_e32 v88, v88
	v_rcp_f32_e32 v85, v85
	v_rcp_f32_e32 v89, v89
	s_mov_b32 vcc_lo, 0x437f0000
	v_pk_mul_f32 v[82:83], v[82:83], vcc op_sel_hi:[1,0]
	v_pk_mul_f32 v[84:85], v[84:85], vcc op_sel_hi:[1,0]
	v_pk_mul_f32 v[86:87], v[86:87], vcc op_sel_hi:[1,0]
	v_pk_mul_f32 v[88:89], v[88:89], vcc op_sel_hi:[1,0]
	v_rndne_f32_e32 v82, v82
	v_rndne_f32_e32 v86, v86
	v_rndne_f32_e32 v83, v83
	v_rndne_f32_e32 v87, v87
	v_rndne_f32_e32 v84, v84
	v_rndne_f32_e32 v88, v88
	v_rndne_f32_e32 v85, v85
	v_rndne_f32_e32 v89, v89
	v_cvt_u32_f32_e32 v82, v82
	v_cvt_u32_f32_e32 v86, v86
	v_cvt_u32_f32_e32 v83, v83
	v_cvt_u32_f32_e32 v87, v87
	v_cvt_u32_f32_sdwa v84, v84 dst_sel:WORD_1 dst_unused:UNUSED_PAD src0_sel:DWORD
	v_cvt_u32_f32_sdwa v88, v88 dst_sel:WORD_1 dst_unused:UNUSED_PAD src0_sel:DWORD
	v_cvt_u32_f32_sdwa v85, v85 dst_sel:BYTE_3 dst_unused:UNUSED_PAD src0_sel:DWORD
	v_cvt_u32_f32_sdwa v89, v89 dst_sel:BYTE_3 dst_unused:UNUSED_PAD src0_sel:DWORD
	v_lshl_or_b32 v82, v83, 8, v82
	v_lshl_or_b32 v83, v87, 8, v86
	v_or3_b32 v82, v82, v84, v85
	v_or3_b32 v83, v83, v88, v89
	v_lshl_add_u64 v[84:85], v[108:109], 0, v[116:117]
	global_store_dwordx2 v[84:85], v[82:83], off

.LBB0_638:
	s_and_b64 vcc, exec, s[50:51]
	s_cbranch_vccz .LBB0_640
	v_add_u32_e32 v86, s10, v146
	v_ashrrev_i32_e32 v87, 31, v86
	v_pk_add_f32 v[74:75], v[116:117], v[228:229]
	v_pk_add_f32 v[76:77], v[102:103], v[230:231]
	v_pk_add_f32 v[78:79], v[120:121], v[232:233]
	v_pk_add_f32 v[80:81], v[118:119], v[234:235]
	s_mov_b32 vcc_lo, 0xbfb8aa3b
	v_pk_mul_f32 v[74:75], v[74:75], vcc op_sel_hi:[1,0]
	v_pk_mul_f32 v[76:77], v[76:77], vcc op_sel_hi:[1,0]
	v_pk_mul_f32 v[78:79], v[78:79], vcc op_sel_hi:[1,0]
	v_pk_mul_f32 v[80:81], v[80:81], vcc op_sel_hi:[1,0]
	v_exp_f32_e32 v74, v74
	v_exp_f32_e32 v78, v78
	v_exp_f32_e32 v75, v75
	v_exp_f32_e32 v79, v79
	v_exp_f32_e32 v76, v76
	v_exp_f32_e32 v80, v80
	v_exp_f32_e32 v77, v77
	v_exp_f32_e32 v81, v81
	s_mov_b32 vcc_lo, 1.0
	v_pk_add_f32 v[74:75], v[74:75], vcc op_sel_hi:[1,0]
	v_pk_add_f32 v[76:77], v[76:77], vcc op_sel_hi:[1,0]
	v_pk_add_f32 v[78:79], v[78:79], vcc op_sel_hi:[1,0]
	v_pk_add_f32 v[80:81], v[80:81], vcc op_sel_hi:[1,0]
	v_rcp_f32_e32 v74, v74
	v_rcp_f32_e32 v78, v78
	v_rcp_f32_e32 v75, v75
	v_rcp_f32_e32 v79, v79
	v_rcp_f32_e32 v76, v76
	v_rcp_f32_e32 v80, v80
	v_rcp_f32_e32 v77, v77
	v_rcp_f32_e32 v81, v81
	s_mov_b32 vcc_lo, 0x437f0000
	v_pk_mul_f32 v[74:75], v[74:75], vcc op_sel_hi:[1,0]
	v_pk_mul_f32 v[76:77], v[76:77], vcc op_sel_hi:[1,0]
	v_pk_mul_f32 v[78:79], v[78:79], vcc op_sel_hi:[1,0]
	v_pk_mul_f32 v[80:81], v[80:81], vcc op_sel_hi:[1,0]
	v_rndne_f32_e32 v74, v74
	v_rndne_f32_e32 v78, v78
	v_rndne_f32_e32 v75, v75
	v_rndne_f32_e32 v79, v79
	v_rndne_f32_e32 v76, v76
	v_rndne_f32_e32 v80, v80
	v_rndne_f32_e32 v77, v77
	v_rndne_f32_e32 v81, v81
	v_cvt_u32_f32_e32 v74, v74
	v_cvt_u32_f32_e32 v78, v78
	v_cvt_u32_f32_e32 v75, v75
	v_cvt_u32_f32_e32 v79, v79
	v_cvt_u32_f32_sdwa v76, v76 dst_sel:WORD_1 dst_unused:UNUSED_PAD src0_sel:DWORD
	v_cvt_u32_f32_sdwa v80, v80 dst_sel:WORD_1 dst_unused:UNUSED_PAD src0_sel:DWORD
	v_cvt_u32_f32_sdwa v77, v77 dst_sel:BYTE_3 dst_unused:UNUSED_PAD src0_sel:DWORD
	v_cvt_u32_f32_sdwa v81, v81 dst_sel:BYTE_3 dst_unused:UNUSED_PAD src0_sel:DWORD
	v_lshl_or_b32 v74, v75, 8, v74
	v_lshl_or_b32 v75, v79, 8, v78
	v_or3_b32 v74, v74, v76, v77
	v_or3_b32 v75, v75, v80, v81
	v_lshl_add_u64 v[76:77], v[92:93], 0, v[86:87]
	global_store_dwordx2 v[76:77], v[74:75], off

.LBB0_700:
	s_and_b64 vcc, exec, s[50:51]
	s_cbranch_vccz .LBB0_702
	v_add_u32_e32 v98, s10, v122
	v_ashrrev_i32_e32 v99, 31, v98
	v_pk_add_f32 v[66:67], v[76:77], v[236:237]
	v_pk_add_f32 v[68:69], v[74:75], v[238:239]
	v_pk_add_f32 v[70:71], v[104:105], v[240:241]
	v_pk_add_f32 v[72:73], v[102:103], v[206:207]
	s_mov_b32 vcc_lo, 0xbfb8aa3b
	v_pk_mul_f32 v[66:67], v[66:67], vcc op_sel_hi:[1,0]
	v_pk_mul_f32 v[68:69], v[68:69], vcc op_sel_hi:[1,0]
	v_pk_mul_f32 v[70:71], v[70:71], vcc op_sel_hi:[1,0]
	v_pk_mul_f32 v[72:73], v[72:73], vcc op_sel_hi:[1,0]
	v_exp_f32_e32 v66, v66
	v_exp_f32_e32 v70, v70
	v_exp_f32_e32 v67, v67
	v_exp_f32_e32 v71, v71
	v_exp_f32_e32 v68, v68
	v_exp_f32_e32 v72, v72
	v_exp_f32_e32 v69, v69
	v_exp_f32_e32 v73, v73
	s_mov_b32 vcc_lo, 1.0
	v_pk_add_f32 v[66:67], v[66:67], vcc op_sel_hi:[1,0]
	v_pk_add_f32 v[68:69], v[68:69], vcc op_sel_hi:[1,0]
	v_pk_add_f32 v[70:71], v[70:71], vcc op_sel_hi:[1,0]
	v_pk_add_f32 v[72:73], v[72:73], vcc op_sel_hi:[1,0]
	v_rcp_f32_e32 v66, v66
	v_rcp_f32_e32 v70, v70
	v_rcp_f32_e32 v67, v67
	v_rcp_f32_e32 v71, v71
	v_rcp_f32_e32 v68, v68
	v_rcp_f32_e32 v72, v72
	v_rcp_f32_e32 v69, v69
	v_rcp_f32_e32 v73, v73
	s_mov_b32 vcc_lo, 0x437f0000
	v_pk_mul_f32 v[66:67], v[66:67], vcc op_sel_hi:[1,0]
	v_pk_mul_f32 v[68:69], v[68:69], vcc op_sel_hi:[1,0]
	v_pk_mul_f32 v[70:71], v[70:71], vcc op_sel_hi:[1,0]
	v_pk_mul_f32 v[72:73], v[72:73], vcc op_sel_hi:[1,0]
	v_rndne_f32_e32 v66, v66
	v_rndne_f32_e32 v70, v70
	v_rndne_f32_e32 v67, v67
	v_rndne_f32_e32 v71, v71
	v_rndne_f32_e32 v68, v68
	v_rndne_f32_e32 v72, v72
	v_rndne_f32_e32 v69, v69
	v_rndne_f32_e32 v73, v73
	v_cvt_u32_f32_e32 v66, v66
	v_cvt_u32_f32_e32 v70, v70
	v_cvt_u32_f32_e32 v67, v67
	v_cvt_u32_f32_e32 v71, v71
	v_cvt_u32_f32_sdwa v68, v68 dst_sel:WORD_1 dst_unused:UNUSED_PAD src0_sel:DWORD
	v_cvt_u32_f32_sdwa v72, v72 dst_sel:WORD_1 dst_unused:UNUSED_PAD src0_sel:DWORD
	v_cvt_u32_f32_sdwa v69, v69 dst_sel:BYTE_3 dst_unused:UNUSED_PAD src0_sel:DWORD
	v_cvt_u32_f32_sdwa v73, v73 dst_sel:BYTE_3 dst_unused:UNUSED_PAD src0_sel:DWORD
	v_lshl_or_b32 v66, v67, 8, v66
	v_lshl_or_b32 v67, v71, 8, v70
	v_or3_b32 v66, v66, v68, v69
	v_or3_b32 v67, v67, v72, v73
	v_lshl_add_u64 v[68:69], v[92:93], 0, v[98:99]
	global_store_dwordx2 v[68:69], v[66:67], off

.LBB0_768:
	s_and_b64 vcc, exec, s[50:51]
	s_cbranch_vccz .LBB0_770
	v_add_u32_e32 v70, s10, v146
	v_ashrrev_i32_e32 v71, 31, v70
	v_pk_add_f32 v[58:59], v[98:99], v[228:229]
	v_pk_add_f32 v[60:61], v[86:87], v[230:231]
	v_pk_add_f32 v[62:63], v[102:103], v[232:233]
	v_pk_add_f32 v[64:65], v[100:101], v[234:235]
	s_mov_b32 vcc_lo, 0xbfb8aa3b
	v_pk_mul_f32 v[58:59], v[58:59], vcc op_sel_hi:[1,0]
	v_pk_mul_f32 v[60:61], v[60:61], vcc op_sel_hi:[1,0]
	v_pk_mul_f32 v[62:63], v[62:63], vcc op_sel_hi:[1,0]
	v_pk_mul_f32 v[64:65], v[64:65], vcc op_sel_hi:[1,0]
	v_exp_f32_e32 v58, v58
	v_exp_f32_e32 v62, v62
	v_exp_f32_e32 v59, v59
	v_exp_f32_e32 v63, v63
	v_exp_f32_e32 v60, v60
	v_exp_f32_e32 v64, v64
	v_exp_f32_e32 v61, v61
	v_exp_f32_e32 v65, v65
	s_mov_b32 vcc_lo, 1.0
	v_pk_add_f32 v[58:59], v[58:59], vcc op_sel_hi:[1,0]
	v_pk_add_f32 v[60:61], v[60:61], vcc op_sel_hi:[1,0]
	v_pk_add_f32 v[62:63], v[62:63], vcc op_sel_hi:[1,0]
	v_pk_add_f32 v[64:65], v[64:65], vcc op_sel_hi:[1,0]
	v_rcp_f32_e32 v58, v58
	v_rcp_f32_e32 v62, v62
	v_rcp_f32_e32 v59, v59
	v_rcp_f32_e32 v63, v63
	v_rcp_f32_e32 v60, v60
	v_rcp_f32_e32 v64, v64
	v_rcp_f32_e32 v61, v61
	v_rcp_f32_e32 v65, v65
	s_mov_b32 vcc_lo, 0x437f0000
	v_pk_mul_f32 v[58:59], v[58:59], vcc op_sel_hi:[1,0]
	v_pk_mul_f32 v[60:61], v[60:61], vcc op_sel_hi:[1,0]
	v_pk_mul_f32 v[62:63], v[62:63], vcc op_sel_hi:[1,0]
	v_pk_mul_f32 v[64:65], v[64:65], vcc op_sel_hi:[1,0]
	v_rndne_f32_e32 v58, v58
	v_rndne_f32_e32 v62, v62
	v_rndne_f32_e32 v59, v59
	v_rndne_f32_e32 v63, v63
	v_rndne_f32_e32 v60, v60
	v_rndne_f32_e32 v64, v64
	v_rndne_f32_e32 v61, v61
	v_rndne_f32_e32 v65, v65
	v_cvt_u32_f32_e32 v58, v58
	v_cvt_u32_f32_e32 v62, v62
	v_cvt_u32_f32_e32 v59, v59
	v_cvt_u32_f32_e32 v63, v63
	v_cvt_u32_f32_sdwa v60, v60 dst_sel:WORD_1 dst_unused:UNUSED_PAD src0_sel:DWORD
	v_cvt_u32_f32_sdwa v64, v64 dst_sel:WORD_1 dst_unused:UNUSED_PAD src0_sel:DWORD
	v_cvt_u32_f32_sdwa v61, v61 dst_sel:BYTE_3 dst_unused:UNUSED_PAD src0_sel:DWORD
	v_cvt_u32_f32_sdwa v65, v65 dst_sel:BYTE_3 dst_unused:UNUSED_PAD src0_sel:DWORD
	v_lshl_or_b32 v58, v59, 8, v58
	v_lshl_or_b32 v59, v63, 8, v62
	v_or3_b32 v58, v58, v60, v61
	v_or3_b32 v59, v59, v64, v65
	v_lshl_add_u64 v[60:61], v[76:77], 0, v[70:71]
	global_store_dwordx2 v[60:61], v[58:59], off

.LBB0_830:
	s_and_b64 vcc, exec, s[50:51]
	s_cbranch_vccz .LBB0_832
	v_add_u32_e32 v82, s10, v122
	v_ashrrev_i32_e32 v83, 31, v82
	v_pk_add_f32 v[50:51], v[60:61], v[236:237]
	v_pk_add_f32 v[52:53], v[58:59], v[238:239]
	v_pk_add_f32 v[54:55], v[88:89], v[240:241]
	v_pk_add_f32 v[56:57], v[86:87], v[206:207]
	s_mov_b32 vcc_lo, 0xbfb8aa3b
	v_pk_mul_f32 v[50:51], v[50:51], vcc op_sel_hi:[1,0]
	v_pk_mul_f32 v[52:53], v[52:53], vcc op_sel_hi:[1,0]
	v_pk_mul_f32 v[54:55], v[54:55], vcc op_sel_hi:[1,0]
	v_pk_mul_f32 v[56:57], v[56:57], vcc op_sel_hi:[1,0]
	v_exp_f32_e32 v50, v50
	v_exp_f32_e32 v54, v54
	v_exp_f32_e32 v51, v51
	v_exp_f32_e32 v55, v55
	v_exp_f32_e32 v52, v52
	v_exp_f32_e32 v56, v56
	v_exp_f32_e32 v53, v53
	v_exp_f32_e32 v57, v57
	s_mov_b32 vcc_lo, 1.0
	v_pk_add_f32 v[50:51], v[50:51], vcc op_sel_hi:[1,0]
	v_pk_add_f32 v[52:53], v[52:53], vcc op_sel_hi:[1,0]
	v_pk_add_f32 v[54:55], v[54:55], vcc op_sel_hi:[1,0]
	v_pk_add_f32 v[56:57], v[56:57], vcc op_sel_hi:[1,0]
	v_rcp_f32_e32 v50, v50
	v_rcp_f32_e32 v54, v54
	v_rcp_f32_e32 v51, v51
	v_rcp_f32_e32 v55, v55
	v_rcp_f32_e32 v52, v52
	v_rcp_f32_e32 v56, v56
	v_rcp_f32_e32 v53, v53
	v_rcp_f32_e32 v57, v57
	s_mov_b32 vcc_lo, 0x437f0000
	v_pk_mul_f32 v[50:51], v[50:51], vcc op_sel_hi:[1,0]
	v_pk_mul_f32 v[52:53], v[52:53], vcc op_sel_hi:[1,0]
	v_pk_mul_f32 v[54:55], v[54:55], vcc op_sel_hi:[1,0]
	v_pk_mul_f32 v[56:57], v[56:57], vcc op_sel_hi:[1,0]
	v_rndne_f32_e32 v50, v50
	v_rndne_f32_e32 v54, v54
	v_rndne_f32_e32 v51, v51
	v_rndne_f32_e32 v55, v55
	v_rndne_f32_e32 v52, v52
	v_rndne_f32_e32 v56, v56
	v_rndne_f32_e32 v53, v53
	v_rndne_f32_e32 v57, v57
	v_cvt_u32_f32_e32 v50, v50
	v_cvt_u32_f32_e32 v54, v54
	v_cvt_u32_f32_e32 v51, v51
	v_cvt_u32_f32_e32 v55, v55
	v_cvt_u32_f32_sdwa v52, v52 dst_sel:WORD_1 dst_unused:UNUSED_PAD src0_sel:DWORD
	v_cvt_u32_f32_sdwa v56, v56 dst_sel:WORD_1 dst_unused:UNUSED_PAD src0_sel:DWORD
	v_cvt_u32_f32_sdwa v53, v53 dst_sel:BYTE_3 dst_unused:UNUSED_PAD src0_sel:DWORD
	v_cvt_u32_f32_sdwa v57, v57 dst_sel:BYTE_3 dst_unused:UNUSED_PAD src0_sel:DWORD
	v_lshl_or_b32 v50, v51, 8, v50
	v_lshl_or_b32 v51, v55, 8, v54
	v_or3_b32 v50, v50, v52, v53
	v_or3_b32 v51, v51, v56, v57
	v_lshl_add_u64 v[52:53], v[76:77], 0, v[82:83]
	global_store_dwordx2 v[52:53], v[50:51], off

.LBB0_898:
	s_and_b64 vcc, exec, s[50:51]
	s_cbranch_vccz .LBB0_900
	v_add_u32_e32 v54, s10, v146
	v_ashrrev_i32_e32 v55, 31, v54
	v_pk_add_f32 v[42:43], v[82:83], v[228:229]
	v_pk_add_f32 v[44:45], v[70:71], v[230:231]
	v_pk_add_f32 v[46:47], v[86:87], v[232:233]
	v_pk_add_f32 v[48:49], v[84:85], v[234:235]
	s_mov_b32 vcc_lo, 0xbfb8aa3b
	v_pk_mul_f32 v[42:43], v[42:43], vcc op_sel_hi:[1,0]
	v_pk_mul_f32 v[44:45], v[44:45], vcc op_sel_hi:[1,0]
	v_pk_mul_f32 v[46:47], v[46:47], vcc op_sel_hi:[1,0]
	v_pk_mul_f32 v[48:49], v[48:49], vcc op_sel_hi:[1,0]
	v_exp_f32_e32 v42, v42
	v_exp_f32_e32 v46, v46
	v_exp_f32_e32 v43, v43
	v_exp_f32_e32 v47, v47
	v_exp_f32_e32 v44, v44
	v_exp_f32_e32 v48, v48
	v_exp_f32_e32 v45, v45
	v_exp_f32_e32 v49, v49
	s_mov_b32 vcc_lo, 1.0
	v_pk_add_f32 v[42:43], v[42:43], vcc op_sel_hi:[1,0]
	v_pk_add_f32 v[44:45], v[44:45], vcc op_sel_hi:[1,0]
	v_pk_add_f32 v[46:47], v[46:47], vcc op_sel_hi:[1,0]
	v_pk_add_f32 v[48:49], v[48:49], vcc op_sel_hi:[1,0]
	v_rcp_f32_e32 v42, v42
	v_rcp_f32_e32 v46, v46
	v_rcp_f32_e32 v43, v43
	v_rcp_f32_e32 v47, v47
	v_rcp_f32_e32 v44, v44
	v_rcp_f32_e32 v48, v48
	v_rcp_f32_e32 v45, v45
	v_rcp_f32_e32 v49, v49
	s_mov_b32 vcc_lo, 0x437f0000
	v_pk_mul_f32 v[42:43], v[42:43], vcc op_sel_hi:[1,0]
	v_pk_mul_f32 v[44:45], v[44:45], vcc op_sel_hi:[1,0]
	v_pk_mul_f32 v[46:47], v[46:47], vcc op_sel_hi:[1,0]
	v_pk_mul_f32 v[48:49], v[48:49], vcc op_sel_hi:[1,0]
	v_rndne_f32_e32 v42, v42
	v_rndne_f32_e32 v46, v46
	v_rndne_f32_e32 v43, v43
	v_rndne_f32_e32 v47, v47
	v_rndne_f32_e32 v44, v44
	v_rndne_f32_e32 v48, v48
	v_rndne_f32_e32 v45, v45
	v_rndne_f32_e32 v49, v49
	v_cvt_u32_f32_e32 v42, v42
	v_cvt_u32_f32_e32 v46, v46
	v_cvt_u32_f32_e32 v43, v43
	v_cvt_u32_f32_e32 v47, v47
	v_cvt_u32_f32_sdwa v44, v44 dst_sel:WORD_1 dst_unused:UNUSED_PAD src0_sel:DWORD
	v_cvt_u32_f32_sdwa v48, v48 dst_sel:WORD_1 dst_unused:UNUSED_PAD src0_sel:DWORD
	v_cvt_u32_f32_sdwa v45, v45 dst_sel:BYTE_3 dst_unused:UNUSED_PAD src0_sel:DWORD
	v_cvt_u32_f32_sdwa v49, v49 dst_sel:BYTE_3 dst_unused:UNUSED_PAD src0_sel:DWORD
	v_lshl_or_b32 v42, v43, 8, v42
	v_lshl_or_b32 v43, v47, 8, v46
	v_or3_b32 v42, v42, v44, v45
	v_or3_b32 v43, v43, v48, v49
	v_lshl_add_u64 v[44:45], v[60:61], 0, v[54:55]
	global_store_dwordx2 v[44:45], v[42:43], off

.LBB0_960:
	s_and_b64 vcc, exec, s[50:51]
	s_cbranch_vccz .LBB0_962
	v_add_u32_e32 v66, s10, v122
	v_ashrrev_i32_e32 v67, 31, v66
	v_pk_add_f32 v[34:35], v[44:45], v[236:237]
	v_pk_add_f32 v[36:37], v[42:43], v[238:239]
	v_pk_add_f32 v[38:39], v[72:73], v[240:241]
	v_pk_add_f32 v[40:41], v[70:71], v[206:207]
	s_mov_b32 vcc_lo, 0xbfb8aa3b
	v_pk_mul_f32 v[34:35], v[34:35], vcc op_sel_hi:[1,0]
	v_pk_mul_f32 v[36:37], v[36:37], vcc op_sel_hi:[1,0]
	v_pk_mul_f32 v[38:39], v[38:39], vcc op_sel_hi:[1,0]
	v_pk_mul_f32 v[40:41], v[40:41], vcc op_sel_hi:[1,0]
	v_exp_f32_e32 v34, v34
	v_exp_f32_e32 v38, v38
	v_exp_f32_e32 v35, v35
	v_exp_f32_e32 v39, v39
	v_exp_f32_e32 v36, v36
	v_exp_f32_e32 v40, v40
	v_exp_f32_e32 v37, v37
	v_exp_f32_e32 v41, v41
	s_mov_b32 vcc_lo, 1.0
	v_pk_add_f32 v[34:35], v[34:35], vcc op_sel_hi:[1,0]
	v_pk_add_f32 v[36:37], v[36:37], vcc op_sel_hi:[1,0]
	v_pk_add_f32 v[38:39], v[38:39], vcc op_sel_hi:[1,0]
	v_pk_add_f32 v[40:41], v[40:41], vcc op_sel_hi:[1,0]
	v_rcp_f32_e32 v34, v34
	v_rcp_f32_e32 v38, v38
	v_rcp_f32_e32 v35, v35
	v_rcp_f32_e32 v39, v39
	v_rcp_f32_e32 v36, v36
	v_rcp_f32_e32 v40, v40
	v_rcp_f32_e32 v37, v37
	v_rcp_f32_e32 v41, v41
	s_mov_b32 vcc_lo, 0x437f0000
	v_pk_mul_f32 v[34:35], v[34:35], vcc op_sel_hi:[1,0]
	v_pk_mul_f32 v[36:37], v[36:37], vcc op_sel_hi:[1,0]
	v_pk_mul_f32 v[38:39], v[38:39], vcc op_sel_hi:[1,0]
	v_pk_mul_f32 v[40:41], v[40:41], vcc op_sel_hi:[1,0]
	v_rndne_f32_e32 v34, v34
	v_rndne_f32_e32 v38, v38
	v_rndne_f32_e32 v35, v35
	v_rndne_f32_e32 v39, v39
	v_rndne_f32_e32 v36, v36
	v_rndne_f32_e32 v40, v40
	v_rndne_f32_e32 v37, v37
	v_rndne_f32_e32 v41, v41
	v_cvt_u32_f32_e32 v34, v34
	v_cvt_u32_f32_e32 v38, v38
	v_cvt_u32_f32_e32 v35, v35
	v_cvt_u32_f32_e32 v39, v39
	v_cvt_u32_f32_sdwa v36, v36 dst_sel:WORD_1 dst_unused:UNUSED_PAD src0_sel:DWORD
	v_cvt_u32_f32_sdwa v40, v40 dst_sel:WORD_1 dst_unused:UNUSED_PAD src0_sel:DWORD
	v_cvt_u32_f32_sdwa v37, v37 dst_sel:BYTE_3 dst_unused:UNUSED_PAD src0_sel:DWORD
	v_cvt_u32_f32_sdwa v41, v41 dst_sel:BYTE_3 dst_unused:UNUSED_PAD src0_sel:DWORD
	v_lshl_or_b32 v34, v35, 8, v34
	v_lshl_or_b32 v35, v39, 8, v38
	v_or3_b32 v34, v34, v36, v37
	v_or3_b32 v35, v35, v40, v41
	v_lshl_add_u64 v[36:37], v[60:61], 0, v[66:67]
	global_store_dwordx2 v[36:37], v[34:35], off

.LBB0_1028:
	s_and_b64 vcc, exec, s[50:51]
	s_cbranch_vccz .LBB0_1030
	v_add_u32_e32 v38, s10, v146
	v_ashrrev_i32_e32 v39, 31, v38
	v_pk_add_f32 v[26:27], v[66:67], v[228:229]
	v_pk_add_f32 v[28:29], v[54:55], v[230:231]
	v_pk_add_f32 v[30:31], v[70:71], v[232:233]
	v_pk_add_f32 v[32:33], v[68:69], v[234:235]
	s_mov_b32 vcc_lo, 0xbfb8aa3b
	v_pk_mul_f32 v[26:27], v[26:27], vcc op_sel_hi:[1,0]
	v_pk_mul_f32 v[28:29], v[28:29], vcc op_sel_hi:[1,0]
	v_pk_mul_f32 v[30:31], v[30:31], vcc op_sel_hi:[1,0]
	v_pk_mul_f32 v[32:33], v[32:33], vcc op_sel_hi:[1,0]
	v_exp_f32_e32 v26, v26
	v_exp_f32_e32 v30, v30
	v_exp_f32_e32 v27, v27
	v_exp_f32_e32 v31, v31
	v_exp_f32_e32 v28, v28
	v_exp_f32_e32 v32, v32
	v_exp_f32_e32 v29, v29
	v_exp_f32_e32 v33, v33
	s_mov_b32 vcc_lo, 1.0
	v_pk_add_f32 v[26:27], v[26:27], vcc op_sel_hi:[1,0]
	v_pk_add_f32 v[28:29], v[28:29], vcc op_sel_hi:[1,0]
	v_pk_add_f32 v[30:31], v[30:31], vcc op_sel_hi:[1,0]
	v_pk_add_f32 v[32:33], v[32:33], vcc op_sel_hi:[1,0]
	v_rcp_f32_e32 v26, v26
	v_rcp_f32_e32 v30, v30
	v_rcp_f32_e32 v27, v27
	v_rcp_f32_e32 v31, v31
	v_rcp_f32_e32 v28, v28
	v_rcp_f32_e32 v32, v32
	v_rcp_f32_e32 v29, v29
	v_rcp_f32_e32 v33, v33
	s_mov_b32 vcc_lo, 0x437f0000
	v_pk_mul_f32 v[26:27], v[26:27], vcc op_sel_hi:[1,0]
	v_pk_mul_f32 v[28:29], v[28:29], vcc op_sel_hi:[1,0]
	v_pk_mul_f32 v[30:31], v[30:31], vcc op_sel_hi:[1,0]
	v_pk_mul_f32 v[32:33], v[32:33], vcc op_sel_hi:[1,0]
	v_rndne_f32_e32 v26, v26
	v_rndne_f32_e32 v30, v30
	v_rndne_f32_e32 v27, v27
	v_rndne_f32_e32 v31, v31
	v_rndne_f32_e32 v28, v28
	v_rndne_f32_e32 v32, v32
	v_rndne_f32_e32 v29, v29
	v_rndne_f32_e32 v33, v33
	v_cvt_u32_f32_e32 v26, v26
	v_cvt_u32_f32_e32 v30, v30
	v_cvt_u32_f32_e32 v27, v27
	v_cvt_u32_f32_e32 v31, v31
	v_cvt_u32_f32_sdwa v28, v28 dst_sel:WORD_1 dst_unused:UNUSED_PAD src0_sel:DWORD
	v_cvt_u32_f32_sdwa v32, v32 dst_sel:WORD_1 dst_unused:UNUSED_PAD src0_sel:DWORD
	v_cvt_u32_f32_sdwa v29, v29 dst_sel:BYTE_3 dst_unused:UNUSED_PAD src0_sel:DWORD
	v_cvt_u32_f32_sdwa v33, v33 dst_sel:BYTE_3 dst_unused:UNUSED_PAD src0_sel:DWORD
	v_lshl_or_b32 v26, v27, 8, v26
	v_lshl_or_b32 v27, v31, 8, v30
	v_or3_b32 v26, v26, v28, v29
	v_or3_b32 v27, v27, v32, v33
	v_lshl_add_u64 v[28:29], v[44:45], 0, v[38:39]
	global_store_dwordx2 v[28:29], v[26:27], off

.LBB0_1090:
	s_and_b64 vcc, exec, s[50:51]
	s_cbranch_vccz .LBB0_1092
	v_add_u32_e32 v50, s10, v122
	v_ashrrev_i32_e32 v51, 31, v50
	v_pk_add_f32 v[18:19], v[28:29], v[236:237]
	v_pk_add_f32 v[20:21], v[26:27], v[238:239]
	v_pk_add_f32 v[22:23], v[56:57], v[240:241]
	v_pk_add_f32 v[24:25], v[54:55], v[206:207]
	s_mov_b32 vcc_lo, 0xbfb8aa3b
	v_pk_mul_f32 v[18:19], v[18:19], vcc op_sel_hi:[1,0]
	v_pk_mul_f32 v[20:21], v[20:21], vcc op_sel_hi:[1,0]
	v_pk_mul_f32 v[22:23], v[22:23], vcc op_sel_hi:[1,0]
	v_pk_mul_f32 v[24:25], v[24:25], vcc op_sel_hi:[1,0]
	v_exp_f32_e32 v18, v18
	v_exp_f32_e32 v22, v22
	v_exp_f32_e32 v19, v19
	v_exp_f32_e32 v23, v23
	v_exp_f32_e32 v20, v20
	v_exp_f32_e32 v24, v24
	v_exp_f32_e32 v21, v21
	v_exp_f32_e32 v25, v25
	s_mov_b32 vcc_lo, 1.0
	v_pk_add_f32 v[18:19], v[18:19], vcc op_sel_hi:[1,0]
	v_pk_add_f32 v[20:21], v[20:21], vcc op_sel_hi:[1,0]
	v_pk_add_f32 v[22:23], v[22:23], vcc op_sel_hi:[1,0]
	v_pk_add_f32 v[24:25], v[24:25], vcc op_sel_hi:[1,0]
	v_rcp_f32_e32 v18, v18
	v_rcp_f32_e32 v22, v22
	v_rcp_f32_e32 v19, v19
	v_rcp_f32_e32 v23, v23
	v_rcp_f32_e32 v20, v20
	v_rcp_f32_e32 v24, v24
	v_rcp_f32_e32 v21, v21
	v_rcp_f32_e32 v25, v25
	s_mov_b32 vcc_lo, 0x437f0000
	v_pk_mul_f32 v[18:19], v[18:19], vcc op_sel_hi:[1,0]
	v_pk_mul_f32 v[20:21], v[20:21], vcc op_sel_hi:[1,0]
	v_pk_mul_f32 v[22:23], v[22:23], vcc op_sel_hi:[1,0]
	v_pk_mul_f32 v[24:25], v[24:25], vcc op_sel_hi:[1,0]
	v_rndne_f32_e32 v18, v18
	v_rndne_f32_e32 v22, v22
	v_rndne_f32_e32 v19, v19
	v_rndne_f32_e32 v23, v23
	v_rndne_f32_e32 v20, v20
	v_rndne_f32_e32 v24, v24
	v_rndne_f32_e32 v21, v21
	v_rndne_f32_e32 v25, v25
	v_cvt_u32_f32_e32 v18, v18
	v_cvt_u32_f32_e32 v22, v22
	v_cvt_u32_f32_e32 v19, v19
	v_cvt_u32_f32_e32 v23, v23
	v_cvt_u32_f32_sdwa v20, v20 dst_sel:WORD_1 dst_unused:UNUSED_PAD src0_sel:DWORD
	v_cvt_u32_f32_sdwa v24, v24 dst_sel:WORD_1 dst_unused:UNUSED_PAD src0_sel:DWORD
	v_cvt_u32_f32_sdwa v21, v21 dst_sel:BYTE_3 dst_unused:UNUSED_PAD src0_sel:DWORD
	v_cvt_u32_f32_sdwa v25, v25 dst_sel:BYTE_3 dst_unused:UNUSED_PAD src0_sel:DWORD
	v_lshl_or_b32 v18, v19, 8, v18
	v_lshl_or_b32 v19, v23, 8, v22
	v_or3_b32 v18, v18, v20, v21
	v_or3_b32 v19, v19, v24, v25
	v_lshl_add_u64 v[20:21], v[44:45], 0, v[50:51]
	global_store_dwordx2 v[20:21], v[18:19], off

.LBB0_1158:
	s_and_b64 vcc, exec, s[28:29]
	s_cbranch_vccz .LBB0_1160
	v_add_u32_e32 v22, s10, v146
	v_ashrrev_i32_e32 v23, 31, v22
	v_pk_add_f32 v[10:11], v[50:51], v[228:229]
	v_pk_add_f32 v[12:13], v[38:39], v[230:231]
	v_pk_add_f32 v[14:15], v[54:55], v[232:233]
	v_pk_add_f32 v[16:17], v[52:53], v[234:235]
	s_mov_b32 vcc_lo, 0xbfb8aa3b
	v_pk_mul_f32 v[10:11], v[10:11], vcc op_sel_hi:[1,0]
	v_pk_mul_f32 v[12:13], v[12:13], vcc op_sel_hi:[1,0]
	v_pk_mul_f32 v[14:15], v[14:15], vcc op_sel_hi:[1,0]
	v_pk_mul_f32 v[16:17], v[16:17], vcc op_sel_hi:[1,0]
	v_exp_f32_e32 v10, v10
	v_exp_f32_e32 v14, v14
	v_exp_f32_e32 v11, v11
	v_exp_f32_e32 v15, v15
	v_exp_f32_e32 v12, v12
	v_exp_f32_e32 v16, v16
	v_exp_f32_e32 v13, v13
	v_exp_f32_e32 v17, v17
	s_mov_b32 vcc_lo, 1.0
	v_pk_add_f32 v[10:11], v[10:11], vcc op_sel_hi:[1,0]
	v_pk_add_f32 v[12:13], v[12:13], vcc op_sel_hi:[1,0]
	v_pk_add_f32 v[14:15], v[14:15], vcc op_sel_hi:[1,0]
	v_pk_add_f32 v[16:17], v[16:17], vcc op_sel_hi:[1,0]
	v_rcp_f32_e32 v10, v10
	v_rcp_f32_e32 v14, v14
	v_rcp_f32_e32 v11, v11
	v_rcp_f32_e32 v15, v15
	v_rcp_f32_e32 v12, v12
	v_rcp_f32_e32 v16, v16
	v_rcp_f32_e32 v13, v13
	v_rcp_f32_e32 v17, v17
	s_mov_b32 vcc_lo, 0x437f0000
	v_pk_mul_f32 v[10:11], v[10:11], vcc op_sel_hi:[1,0]
	v_pk_mul_f32 v[12:13], v[12:13], vcc op_sel_hi:[1,0]
	v_pk_mul_f32 v[14:15], v[14:15], vcc op_sel_hi:[1,0]
	v_pk_mul_f32 v[16:17], v[16:17], vcc op_sel_hi:[1,0]
	v_rndne_f32_e32 v10, v10
	v_rndne_f32_e32 v14, v14
	v_rndne_f32_e32 v11, v11
	v_rndne_f32_e32 v15, v15
	v_rndne_f32_e32 v12, v12
	v_rndne_f32_e32 v16, v16
	v_rndne_f32_e32 v13, v13
	v_rndne_f32_e32 v17, v17
	v_cvt_u32_f32_e32 v10, v10
	v_cvt_u32_f32_e32 v14, v14
	v_cvt_u32_f32_e32 v11, v11
	v_cvt_u32_f32_e32 v15, v15
	v_cvt_u32_f32_sdwa v12, v12 dst_sel:WORD_1 dst_unused:UNUSED_PAD src0_sel:DWORD
	v_cvt_u32_f32_sdwa v16, v16 dst_sel:WORD_1 dst_unused:UNUSED_PAD src0_sel:DWORD
	v_cvt_u32_f32_sdwa v13, v13 dst_sel:BYTE_3 dst_unused:UNUSED_PAD src0_sel:DWORD
	v_cvt_u32_f32_sdwa v17, v17 dst_sel:BYTE_3 dst_unused:UNUSED_PAD src0_sel:DWORD
	v_lshl_or_b32 v10, v11, 8, v10
	v_lshl_or_b32 v11, v15, 8, v14
	v_or3_b32 v10, v10, v12, v13
	v_or3_b32 v11, v11, v16, v17
	v_lshl_add_u64 v[12:13], v[28:29], 0, v[22:23]
	global_store_dwordx2 v[12:13], v[10:11], off

.LBB0_1221:
	s_and_b64 vcc, exec, s[20:21]
	s_cbranch_vccz .LBB0_1223
	v_add_u32_e32 v34, s10, v122
	v_ashrrev_i32_e32 v35, 31, v34
	v_pk_add_f32 v[2:3], v[12:13], v[236:237]
	v_pk_add_f32 v[4:5], v[10:11], v[238:239]
	v_pk_add_f32 v[6:7], v[40:41], v[240:241]
	v_pk_add_f32 v[8:9], v[38:39], v[206:207]
	s_mov_b32 vcc_lo, 0xbfb8aa3b
	v_pk_mul_f32 v[2:3], v[2:3], vcc op_sel_hi:[1,0]
	v_pk_mul_f32 v[4:5], v[4:5], vcc op_sel_hi:[1,0]
	v_pk_mul_f32 v[6:7], v[6:7], vcc op_sel_hi:[1,0]
	v_pk_mul_f32 v[8:9], v[8:9], vcc op_sel_hi:[1,0]
	v_exp_f32_e32 v2, v2
	v_exp_f32_e32 v6, v6
	v_exp_f32_e32 v3, v3
	v_exp_f32_e32 v7, v7
	v_exp_f32_e32 v4, v4
	v_exp_f32_e32 v8, v8
	v_exp_f32_e32 v5, v5
	v_exp_f32_e32 v9, v9
	s_mov_b32 vcc_lo, 1.0
	v_pk_add_f32 v[2:3], v[2:3], vcc op_sel_hi:[1,0]
	v_pk_add_f32 v[4:5], v[4:5], vcc op_sel_hi:[1,0]
	v_pk_add_f32 v[6:7], v[6:7], vcc op_sel_hi:[1,0]
	v_pk_add_f32 v[8:9], v[8:9], vcc op_sel_hi:[1,0]
	v_rcp_f32_e32 v2, v2
	v_rcp_f32_e32 v6, v6
	v_rcp_f32_e32 v3, v3
	v_rcp_f32_e32 v7, v7
	v_rcp_f32_e32 v4, v4
	v_rcp_f32_e32 v8, v8
	v_rcp_f32_e32 v5, v5
	v_rcp_f32_e32 v9, v9
	s_mov_b32 vcc_lo, 0x437f0000
	v_pk_mul_f32 v[2:3], v[2:3], vcc op_sel_hi:[1,0]
	v_pk_mul_f32 v[4:5], v[4:5], vcc op_sel_hi:[1,0]
	v_pk_mul_f32 v[6:7], v[6:7], vcc op_sel_hi:[1,0]
	v_pk_mul_f32 v[8:9], v[8:9], vcc op_sel_hi:[1,0]
	v_rndne_f32_e32 v2, v2
	v_rndne_f32_e32 v6, v6
	v_rndne_f32_e32 v3, v3
	v_rndne_f32_e32 v7, v7
	v_rndne_f32_e32 v4, v4
	v_rndne_f32_e32 v8, v8
	v_rndne_f32_e32 v5, v5
	v_rndne_f32_e32 v9, v9
	v_cvt_u32_f32_e32 v2, v2
	v_cvt_u32_f32_e32 v6, v6
	v_cvt_u32_f32_e32 v3, v3
	v_cvt_u32_f32_e32 v7, v7
	v_cvt_u32_f32_sdwa v4, v4 dst_sel:WORD_1 dst_unused:UNUSED_PAD src0_sel:DWORD
	v_cvt_u32_f32_sdwa v8, v8 dst_sel:WORD_1 dst_unused:UNUSED_PAD src0_sel:DWORD
	v_cvt_u32_f32_sdwa v5, v5 dst_sel:BYTE_3 dst_unused:UNUSED_PAD src0_sel:DWORD
	v_cvt_u32_f32_sdwa v9, v9 dst_sel:BYTE_3 dst_unused:UNUSED_PAD src0_sel:DWORD
	v_lshl_or_b32 v2, v3, 8, v2
	v_lshl_or_b32 v3, v7, 8, v6
	v_or3_b32 v2, v2, v4, v5
	v_or3_b32 v3, v3, v8, v9
	v_lshl_add_u64 v[4:5], v[28:29], 0, v[34:35]
	global_store_dwordx2 v[4:5], v[2:3], off
